# scan compute loop: back edge taken before the chunk barrier (barrier is the first instruction of the body)
# speedup vs baseline: 1.0191x; 1.0082x over previous
.LBB0_1047:
	s_and_b64 vcc, exec, s[24:25]
	s_cbranch_vccz .LBB0_1279
	s_waitcnt vmcnt(0)
	v_mov_b32_e32 v4, v232
	s_nop 0
	v_ashrrev_i32_e32 v0, 6, v4
	v_and_b32_e32 v54, 15, v4
	v_cmp_gt_i32_e32 vcc, 4, v0
	v_lshlrev_b32_e32 v38, 2, v54
	s_barrier
	s_and_saveexec_b64 s[24:25], vcc
	s_xor_b64 s[24:25], exec, s[24:25]
	s_cbranch_execz .LBB0_1051
	v_lshlrev_b32_e32 v2, 2, v4
	s_waitcnt lgkmcnt(0)
	s_barrier
	v_and_b32_e32 v2, 0xc0, v2
	v_lshl_or_b32 v85, v0, 8, v2
	v_mov_b32_e32 v74, 0
	v_lshlrev_b32_e32 v83, 4, v54
	v_add3_u32 v87, 0, v85, v38
	s_mov_b32 s26, 0
	s_mov_b32 s96, 0x12800
	v_mov_b32_e32 v75, v74
	v_mov_b32_e32 v76, v74
	v_mov_b32_e32 v77, v74
	v_add_u32_e32 v88, 0x12800, v83
	ds_read_b128 v[108:111], v88 offset:4096
	ds_read_b128 v[100:103], v88
	ds_read_b128 v[120:123], v88 offset:8192
	ds_read_b128 v[112:115], v88 offset:4352
	ds_read_b128 v[104:107], v88 offset:256
	ds_read_b128 v[128:131], v88 offset:8448
	ds_read_b128 v[124:127], v88 offset:4608
	ds_read_b128 v[116:119], v88 offset:512
	s_waitcnt lgkmcnt(0)
	s_and_b32 s2, s26, 1
	s_mul_i32 s3, s2, 0x5400
	v_lshlrev_b32_e32 v91, 2, v87
	v_lshl_add_u32 v91, s2, 14, v91
	s_add_i32 s2, s3, 0
	v_add_u32_e32 v0, s2, v85
	v_add_u32_e32 v89, s2, v83
	v_add_u32_e32 v90, s96, v83
	s_add_i32 s96, s96, 0x3000
	s_cmp_eq_u32 s96, 0x1e800
	s_cselect_b32 s96, 0x20200, s96
	s_cmp_eq_u32 s96, 0x23200
	s_cselect_b32 s96, 0x12800, s96
	v_add_u32_e32 v88, s96, v83
	s_setprio 3
	s_branch .Lscan_compute_entry
.LBB0_1050:
	s_barrier
.Lscan_compute_entry:
	ds_read_b128 v[14:17], v0 offset:20480
	ds_read_b128 v[10:13], v0 offset:20496
	ds_read_b128 v[6:9], v0 offset:20512
	ds_read_b128 v[2:5], v0 offset:20528
	ds_read_b128 v[54:57], v89 offset:16384
	ds_read_b128 v[26:29], v89 offset:16640
	ds_read_b128 v[78:81], v89 offset:4096
	ds_read_b128 v[58:61], v89 offset:4352
	ds_read_b128 v[30:33], v89 offset:4608
	ds_read_b128 v[22:25], v90 offset:8704
	ds_read_b128 v[18:21], v89 offset:16896
	v_pk_mul_f32 v[66:67], v[74:75], v[108:109]
	s_waitcnt lgkmcnt(4)
	v_pk_mul_f32 v[78:79], v[14:15], v[78:79] op_sel_hi:[0,1]
	v_pk_fma_f32 v[66:67], v[76:77], v[110:111], v[66:67]
	v_pk_mul_f32 v[80:81], v[14:15], v[80:81] op_sel_hi:[0,1]
	v_add_f32_e32 v66, v66, v67
	v_pk_fma_f32 v[62:63], v[74:75], v[100:101], v[78:79]
	v_pk_fma_f32 v[64:65], v[76:77], v[102:103], v[80:81]
	v_add_f32_dpp v66, v66, v66 quad_perm:[1,0,3,2] row_mask:0xf bank_mask:0xf bound_ctrl:1
	v_mov_b32_e32 v0, v17
	v_mov_b32_e32 v82, v13
	v_add_f32_dpp v66, v66, v66 quad_perm:[2,3,0,1] row_mask:0xf bank_mask:0xf bound_ctrl:1
	v_mov_b32_e32 v84, v9
	v_mov_b32_e32 v86, v5
	v_add_f32_dpp v66, v66, v66 row_half_mirror row_mask:0xf bank_mask:0xf bound_ctrl:1
	s_add_i32 s26, s26, 1
	s_nop 0
	v_add_f32_dpp v66, v66, v66 row_ror:8 row_mask:0xf bank_mask:0xf bound_ctrl:1
	v_pk_fma_f32 v[62:63], v[120:121], v[66:67], v[62:63] op_sel_hi:[1,0,1] neg_lo:[1,0,0] neg_hi:[1,0,0]
	v_pk_fma_f32 v[64:65], v[122:123], v[66:67], v[64:65] op_sel_hi:[1,0,1] neg_lo:[1,0,0] neg_hi:[1,0,0]
	v_pk_mul_f32 v[50:51], v[112:113], v[62:63]
	v_pk_mul_f32 v[46:47], v[104:105], v[62:63]
	v_pk_fma_f32 v[50:51], v[114:115], v[64:65], v[50:51]
	s_waitcnt lgkmcnt(3)
	v_pk_fma_f32 v[66:67], v[14:15], v[58:59], v[46:47] op_sel:[1,0,0]
	v_add_f32_e32 v47, v50, v51
	v_pk_mul_f32 v[48:49], v[106:107], v[64:65]
	v_pk_mul_f32 v[56:57], v[56:57], v[64:65]
	v_add_f32_dpp v68, v47, v47 quad_perm:[1,0,3,2] row_mask:0xf bank_mask:0xf bound_ctrl:1
	v_pk_fma_f32 v[14:15], v[14:15], v[60:61], v[48:49] op_sel:[1,0,0]
	v_pk_fma_f32 v[54:55], v[54:55], v[62:63], v[56:57]
	v_add_f32_dpp v68, v68, v68 quad_perm:[2,3,0,1] row_mask:0xf bank_mask:0xf bound_ctrl:1
	v_add_f32_e32 v92, v54, v55
	s_nop 0
	v_add_f32_dpp v68, v68, v68 row_half_mirror row_mask:0xf bank_mask:0xf bound_ctrl:1
	ds_read_b128 v[46:49], v90 offset:768
	ds_read_b128 v[50:53], v89 offset:4864
	ds_read_b128 v[54:57], v90 offset:4864
	ds_read_b128 v[58:61], v90 offset:8960
	ds_read_b128 v[62:65], v89 offset:17152
	v_add_f32_dpp v68, v68, v68 row_ror:8 row_mask:0xf bank_mask:0xf bound_ctrl:1
	v_pk_fma_f32 v[42:43], v[128:129], v[68:69], v[66:67] op_sel_hi:[1,0,1] neg_lo:[1,0,0] neg_hi:[1,0,0]
	v_pk_fma_f32 v[14:15], v[130:131], v[68:69], v[14:15] op_sel_hi:[1,0,1] neg_lo:[1,0,0] neg_hi:[1,0,0]
	v_pk_mul_f32 v[38:39], v[124:125], v[42:43]
	v_pk_mul_f32 v[28:29], v[28:29], v[14:15]
	v_pk_mul_f32 v[36:37], v[118:119], v[14:15]
	v_pk_fma_f32 v[14:15], v[126:127], v[14:15], v[38:39]
	v_pk_mul_f32 v[34:35], v[116:117], v[42:43]
	v_add_f32_e32 v14, v14, v15
	v_pk_fma_f32 v[26:27], v[26:27], v[42:43], v[28:29]
	s_waitcnt lgkmcnt(7)
	v_pk_fma_f32 v[42:43], v[16:17], v[30:31], v[34:35] op_sel_hi:[0,1,1]
	v_add_f32_dpp v66, v14, v14 quad_perm:[1,0,3,2] row_mask:0xf bank_mask:0xf bound_ctrl:1
	v_pk_fma_f32 v[44:45], v[16:17], v[32:33], v[36:37] op_sel_hi:[0,1,1]
	v_add_f32_e32 v93, v26, v27
	v_add_f32_dpp v66, v66, v66 quad_perm:[2,3,0,1] row_mask:0xf bank_mask:0xf bound_ctrl:1
	ds_read_b128 v[14:17], v90 offset:1024
	ds_read_b128 v[26:29], v89 offset:5120
	ds_read_b128 v[30:33], v90 offset:5120
	ds_read_b128 v[34:37], v90 offset:9216
	ds_read_b128 v[38:41], v89 offset:17408
	v_add_f32_dpp v66, v66, v66 row_half_mirror row_mask:0xf bank_mask:0xf bound_ctrl:1
	s_nop 1
	v_add_f32_dpp v66, v66, v66 row_ror:8 row_mask:0xf bank_mask:0xf bound_ctrl:1
	s_waitcnt lgkmcnt(11)
	v_pk_fma_f32 v[22:23], v[22:23], v[66:67], v[42:43] op_sel_hi:[1,0,1] neg_lo:[1,0,0] neg_hi:[1,0,0]
	v_pk_fma_f32 v[24:25], v[24:25], v[66:67], v[44:45] op_sel_hi:[1,0,1] neg_lo:[1,0,0] neg_hi:[1,0,0]
	s_waitcnt lgkmcnt(7)
	v_pk_mul_f32 v[42:43], v[54:55], v[22:23]
	v_pk_mul_f32 v[20:21], v[20:21], v[24:25]
	v_pk_mul_f32 v[44:45], v[46:47], v[22:23]
	v_pk_mul_f32 v[46:47], v[48:49], v[24:25]
	v_pk_fma_f32 v[18:19], v[18:19], v[22:23], v[20:21]
	v_pk_fma_f32 v[20:21], v[56:57], v[24:25], v[42:43]
	v_pk_fma_f32 v[54:55], v[0:1], v[50:51], v[44:45] op_sel_hi:[0,1,1]
	v_pk_fma_f32 v[56:57], v[0:1], v[52:53], v[46:47] op_sel_hi:[0,1,1]
	v_add_f32_e32 v94, v18, v19
	v_add_f32_e32 v18, v20, v21
	s_nop 0
	s_nop 0
	v_add_f32_dpp v0, v18, v18 quad_perm:[1,0,3,2] row_mask:0xf bank_mask:0xf bound_ctrl:1
	ds_read_b128 v[18:21], v90 offset:1280
	ds_read_b128 v[22:25], v89 offset:5376
	v_add_f32_dpp v0, v0, v0 quad_perm:[2,3,0,1] row_mask:0xf bank_mask:0xf bound_ctrl:1
	ds_read_b128 v[42:45], v90 offset:5376
	ds_read_b128 v[46:49], v90 offset:9472
	v_add_f32_dpp v0, v0, v0 row_half_mirror row_mask:0xf bank_mask:0xf bound_ctrl:1
	ds_read_b128 v[50:53], v89 offset:17664
	s_nop 0
	v_add_f32_dpp v0, v0, v0 row_ror:8 row_mask:0xf bank_mask:0xf bound_ctrl:1
	s_waitcnt lgkmcnt(11)
	v_pk_fma_f32 v[54:55], v[58:59], v[0:1], v[54:55] op_sel_hi:[1,0,1] neg_lo:[1,0,0] neg_hi:[1,0,0]
	v_pk_fma_f32 v[56:57], v[60:61], v[0:1], v[56:57] op_sel_hi:[1,0,1] neg_lo:[1,0,0] neg_hi:[1,0,0]
	s_waitcnt lgkmcnt(7)
	v_pk_mul_f32 v[30:31], v[30:31], v[54:55]
	v_pk_mul_f32 v[58:59], v[64:65], v[56:57]
	v_pk_mul_f32 v[14:15], v[14:15], v[54:55]
	v_pk_fma_f32 v[54:55], v[62:63], v[54:55], v[58:59]
	v_pk_fma_f32 v[30:31], v[32:33], v[56:57], v[30:31]
	v_pk_fma_f32 v[62:63], v[10:11], v[26:27], v[14:15] op_sel_hi:[0,1,1]
	v_add_f32_e32 v95, v54, v55
	v_add_f32_e32 v14, v30, v31
	ds_write_b128 v91, v[92:95] offset:43008
	v_pk_mul_f32 v[16:17], v[16:17], v[56:57]
	v_add_f32_dpp v0, v14, v14 quad_perm:[1,0,3,2] row_mask:0xf bank_mask:0xf bound_ctrl:1
	v_pk_fma_f32 v[64:65], v[10:11], v[28:29], v[16:17] op_sel_hi:[0,1,1]
	ds_read_b128 v[14:17], v90 offset:1536
	v_add_f32_dpp v0, v0, v0 quad_perm:[2,3,0,1] row_mask:0xf bank_mask:0xf bound_ctrl:1
	ds_read_b128 v[26:29], v89 offset:5632
	ds_read_b128 v[30:33], v90 offset:5632
	v_add_f32_dpp v0, v0, v0 row_half_mirror row_mask:0xf bank_mask:0xf bound_ctrl:1
	ds_read_b128 v[54:57], v90 offset:9728
	ds_read_b128 v[58:61], v89 offset:17920
	v_add_f32_dpp v0, v0, v0 row_ror:8 row_mask:0xf bank_mask:0xf bound_ctrl:1
	s_waitcnt lgkmcnt(12)
	v_pk_fma_f32 v[34:35], v[34:35], v[0:1], v[62:63] op_sel_hi:[1,0,1] neg_lo:[1,0,0] neg_hi:[1,0,0]
	v_pk_fma_f32 v[36:37], v[36:37], v[0:1], v[64:65] op_sel_hi:[1,0,1] neg_lo:[1,0,0] neg_hi:[1,0,0]
	s_waitcnt lgkmcnt(8)
	v_pk_mul_f32 v[42:43], v[42:43], v[34:35]
	v_pk_mul_f32 v[40:41], v[40:41], v[36:37]
	v_pk_mul_f32 v[18:19], v[18:19], v[34:35]
	v_pk_mul_f32 v[20:21], v[20:21], v[36:37]
	v_pk_fma_f32 v[34:35], v[38:39], v[34:35], v[40:41]
	v_pk_fma_f32 v[36:37], v[44:45], v[36:37], v[42:43]
	v_pk_fma_f32 v[62:63], v[10:11], v[22:23], v[18:19] op_sel:[1,0,0]
	v_add_f32_e32 v18, v36, v37
	v_add_f32_e32 v96, v34, v35
	v_pk_fma_f32 v[10:11], v[10:11], v[24:25], v[20:21] op_sel:[1,0,0]
	v_add_f32_dpp v0, v18, v18 quad_perm:[1,0,3,2] row_mask:0xf bank_mask:0xf bound_ctrl:1
	ds_read_b128 v[18:21], v90 offset:1792
	ds_read_b128 v[22:25], v89 offset:5888
	v_add_f32_dpp v0, v0, v0 quad_perm:[2,3,0,1] row_mask:0xf bank_mask:0xf bound_ctrl:1
	ds_read_b128 v[34:37], v90 offset:5888
	ds_read_b128 v[38:41], v90 offset:9984
	v_add_f32_dpp v0, v0, v0 row_half_mirror row_mask:0xf bank_mask:0xf bound_ctrl:1
	ds_read_b128 v[42:45], v89 offset:18176
	s_nop 0
	v_add_f32_dpp v0, v0, v0 row_ror:8 row_mask:0xf bank_mask:0xf bound_ctrl:1
	s_waitcnt lgkmcnt(12)
	v_pk_fma_f32 v[46:47], v[46:47], v[0:1], v[62:63] op_sel_hi:[1,0,1] neg_lo:[1,0,0] neg_hi:[1,0,0]
	v_pk_fma_f32 v[10:11], v[48:49], v[0:1], v[10:11] op_sel_hi:[1,0,1] neg_lo:[1,0,0] neg_hi:[1,0,0]
	s_waitcnt lgkmcnt(7)
	v_pk_mul_f32 v[30:31], v[30:31], v[46:47]
	v_pk_mul_f32 v[48:49], v[52:53], v[10:11]
	v_pk_mul_f32 v[14:15], v[14:15], v[46:47]
	v_pk_mul_f32 v[16:17], v[16:17], v[10:11]
	v_pk_fma_f32 v[46:47], v[50:51], v[46:47], v[48:49]
	v_pk_fma_f32 v[10:11], v[32:33], v[10:11], v[30:31]
	v_add_f32_e32 v10, v10, v11
	v_add_f32_e32 v97, v46, v47
	v_pk_fma_f32 v[50:51], v[12:13], v[26:27], v[14:15] op_sel_hi:[0,1,1]
	v_add_f32_dpp v0, v10, v10 quad_perm:[1,0,3,2] row_mask:0xf bank_mask:0xf bound_ctrl:1
	v_pk_fma_f32 v[52:53], v[12:13], v[28:29], v[16:17] op_sel_hi:[0,1,1]
	ds_read_b128 v[10:13], v90 offset:2048
	v_add_f32_dpp v0, v0, v0 quad_perm:[2,3,0,1] row_mask:0xf bank_mask:0xf bound_ctrl:1
	ds_read_b128 v[14:17], v89 offset:6144
	ds_read_b128 v[26:29], v90 offset:6144
	v_add_f32_dpp v0, v0, v0 row_half_mirror row_mask:0xf bank_mask:0xf bound_ctrl:1
	ds_read_b128 v[30:33], v90 offset:10240
	ds_read_b128 v[46:49], v89 offset:18432
	v_add_f32_dpp v0, v0, v0 row_ror:8 row_mask:0xf bank_mask:0xf bound_ctrl:1
	s_waitcnt lgkmcnt(11)
	v_pk_fma_f32 v[50:51], v[54:55], v[0:1], v[50:51] op_sel_hi:[1,0,1] neg_lo:[1,0,0] neg_hi:[1,0,0]
	v_pk_fma_f32 v[52:53], v[56:57], v[0:1], v[52:53] op_sel_hi:[1,0,1] neg_lo:[1,0,0] neg_hi:[1,0,0]
	s_waitcnt lgkmcnt(7)
	v_pk_mul_f32 v[34:35], v[34:35], v[50:51]
	v_pk_mul_f32 v[54:55], v[60:61], v[52:53]
	v_pk_mul_f32 v[18:19], v[18:19], v[50:51]
	v_pk_fma_f32 v[50:51], v[58:59], v[50:51], v[54:55]
	v_pk_fma_f32 v[34:35], v[36:37], v[52:53], v[34:35]
	v_pk_fma_f32 v[58:59], v[82:83], v[22:23], v[18:19] op_sel_hi:[0,1,1]
	v_add_f32_e32 v18, v34, v35
	v_add_f32_e32 v98, v50, v51
	v_pk_mul_f32 v[20:21], v[20:21], v[52:53]
	v_add_f32_dpp v0, v18, v18 quad_perm:[1,0,3,2] row_mask:0xf bank_mask:0xf bound_ctrl:1
	v_pk_fma_f32 v[60:61], v[82:83], v[24:25], v[20:21] op_sel_hi:[0,1,1]
	ds_read_b128 v[18:21], v90 offset:2304
	v_add_f32_dpp v0, v0, v0 quad_perm:[2,3,0,1] row_mask:0xf bank_mask:0xf bound_ctrl:1
	ds_read_b128 v[22:25], v89 offset:6400
	ds_read_b128 v[34:37], v90 offset:6400
	v_add_f32_dpp v0, v0, v0 row_half_mirror row_mask:0xf bank_mask:0xf bound_ctrl:1
	ds_read_b128 v[50:53], v90 offset:10496
	ds_read_b128 v[54:57], v89 offset:18688
	v_add_f32_dpp v0, v0, v0 row_ror:8 row_mask:0xf bank_mask:0xf bound_ctrl:1
	s_waitcnt lgkmcnt(11)
	v_pk_fma_f32 v[38:39], v[38:39], v[0:1], v[58:59] op_sel_hi:[1,0,1] neg_lo:[1,0,0] neg_hi:[1,0,0]
	v_pk_fma_f32 v[40:41], v[40:41], v[0:1], v[60:61] op_sel_hi:[1,0,1] neg_lo:[1,0,0] neg_hi:[1,0,0]
	s_waitcnt lgkmcnt(7)
	v_pk_mul_f32 v[26:27], v[26:27], v[38:39]
	v_pk_mul_f32 v[44:45], v[44:45], v[40:41]
	v_pk_mul_f32 v[10:11], v[10:11], v[38:39]
	v_pk_fma_f32 v[38:39], v[42:43], v[38:39], v[44:45]
	v_pk_fma_f32 v[26:27], v[28:29], v[40:41], v[26:27]
	v_pk_fma_f32 v[58:59], v[6:7], v[14:15], v[10:11] op_sel_hi:[0,1,1]
	v_add_f32_e32 v99, v38, v39
	v_add_f32_e32 v10, v26, v27
	ds_write_b128 v91, v[96:99] offset:47104
	v_pk_mul_f32 v[12:13], v[12:13], v[40:41]
	v_add_f32_dpp v0, v10, v10 quad_perm:[1,0,3,2] row_mask:0xf bank_mask:0xf bound_ctrl:1
	v_pk_fma_f32 v[60:61], v[6:7], v[16:17], v[12:13] op_sel_hi:[0,1,1]
	ds_read_b128 v[10:13], v90 offset:2560
	v_add_f32_dpp v0, v0, v0 quad_perm:[2,3,0,1] row_mask:0xf bank_mask:0xf bound_ctrl:1
	ds_read_b128 v[14:17], v89 offset:6656
	ds_read_b128 v[26:29], v90 offset:6656
	v_add_f32_dpp v0, v0, v0 row_half_mirror row_mask:0xf bank_mask:0xf bound_ctrl:1
	ds_read_b128 v[38:41], v90 offset:10752
	ds_read_b128 v[42:45], v89 offset:18944
	v_add_f32_dpp v0, v0, v0 row_ror:8 row_mask:0xf bank_mask:0xf bound_ctrl:1
	s_waitcnt lgkmcnt(12)
	v_pk_fma_f32 v[30:31], v[30:31], v[0:1], v[58:59] op_sel_hi:[1,0,1] neg_lo:[1,0,0] neg_hi:[1,0,0]
	v_pk_fma_f32 v[32:33], v[32:33], v[0:1], v[60:61] op_sel_hi:[1,0,1] neg_lo:[1,0,0] neg_hi:[1,0,0]
	s_waitcnt lgkmcnt(8)
	v_pk_mul_f32 v[34:35], v[34:35], v[30:31]
	v_pk_mul_f32 v[48:49], v[48:49], v[32:33]
	v_pk_mul_f32 v[18:19], v[18:19], v[30:31]
	v_pk_mul_f32 v[20:21], v[20:21], v[32:33]
	v_pk_fma_f32 v[30:31], v[46:47], v[30:31], v[48:49]
	v_pk_fma_f32 v[32:33], v[36:37], v[32:33], v[34:35]
	v_pk_fma_f32 v[58:59], v[6:7], v[22:23], v[18:19] op_sel:[1,0,0]
	v_add_f32_e32 v18, v32, v33
	v_add_f32_e32 v92, v30, v31
	v_pk_fma_f32 v[6:7], v[6:7], v[24:25], v[20:21] op_sel:[1,0,0]
	v_add_f32_dpp v0, v18, v18 quad_perm:[1,0,3,2] row_mask:0xf bank_mask:0xf bound_ctrl:1
	ds_read_b128 v[18:21], v90 offset:2816
	ds_read_b128 v[22:25], v89 offset:6912
	v_add_f32_dpp v0, v0, v0 quad_perm:[2,3,0,1] row_mask:0xf bank_mask:0xf bound_ctrl:1
	ds_read_b128 v[30:33], v90 offset:6912
	ds_read_b128 v[34:37], v90 offset:11008
	v_add_f32_dpp v0, v0, v0 row_half_mirror row_mask:0xf bank_mask:0xf bound_ctrl:1
	ds_read_b128 v[46:49], v89 offset:19200
	s_nop 0
	v_add_f32_dpp v0, v0, v0 row_ror:8 row_mask:0xf bank_mask:0xf bound_ctrl:1
	s_waitcnt lgkmcnt(12)
	v_pk_fma_f32 v[50:51], v[50:51], v[0:1], v[58:59] op_sel_hi:[1,0,1] neg_lo:[1,0,0] neg_hi:[1,0,0]
	v_pk_fma_f32 v[6:7], v[52:53], v[0:1], v[6:7] op_sel_hi:[1,0,1] neg_lo:[1,0,0] neg_hi:[1,0,0]
	s_waitcnt lgkmcnt(7)
	v_pk_mul_f32 v[26:27], v[26:27], v[50:51]
	v_pk_mul_f32 v[52:53], v[56:57], v[6:7]
	v_pk_mul_f32 v[10:11], v[10:11], v[50:51]
	v_pk_mul_f32 v[12:13], v[12:13], v[6:7]
	v_pk_fma_f32 v[50:51], v[54:55], v[50:51], v[52:53]
	v_pk_fma_f32 v[6:7], v[28:29], v[6:7], v[26:27]
	v_add_f32_e32 v6, v6, v7
	v_add_f32_e32 v93, v50, v51
	v_pk_fma_f32 v[54:55], v[8:9], v[14:15], v[10:11] op_sel_hi:[0,1,1]
	v_add_f32_dpp v0, v6, v6 quad_perm:[1,0,3,2] row_mask:0xf bank_mask:0xf bound_ctrl:1
	v_pk_fma_f32 v[56:57], v[8:9], v[16:17], v[12:13] op_sel_hi:[0,1,1]
	ds_read_b128 v[6:9], v90 offset:3072
	v_add_f32_dpp v0, v0, v0 quad_perm:[2,3,0,1] row_mask:0xf bank_mask:0xf bound_ctrl:1
	ds_read_b128 v[10:13], v89 offset:7168
	ds_read_b128 v[14:17], v90 offset:7168
	v_add_f32_dpp v0, v0, v0 row_half_mirror row_mask:0xf bank_mask:0xf bound_ctrl:1
	ds_read_b128 v[26:29], v90 offset:11264
	ds_read_b128 v[50:53], v89 offset:19456
	v_add_f32_dpp v0, v0, v0 row_ror:8 row_mask:0xf bank_mask:0xf bound_ctrl:1
	s_waitcnt lgkmcnt(11)
	v_pk_fma_f32 v[38:39], v[38:39], v[0:1], v[54:55] op_sel_hi:[1,0,1] neg_lo:[1,0,0] neg_hi:[1,0,0]
	v_pk_fma_f32 v[40:41], v[40:41], v[0:1], v[56:57] op_sel_hi:[1,0,1] neg_lo:[1,0,0] neg_hi:[1,0,0]
	s_waitcnt lgkmcnt(7)
	v_pk_mul_f32 v[30:31], v[30:31], v[38:39]
	v_pk_mul_f32 v[44:45], v[44:45], v[40:41]
	v_pk_mul_f32 v[18:19], v[18:19], v[38:39]
	v_pk_fma_f32 v[38:39], v[42:43], v[38:39], v[44:45]
	v_pk_fma_f32 v[30:31], v[32:33], v[40:41], v[30:31]
	v_pk_fma_f32 v[54:55], v[84:85], v[22:23], v[18:19] op_sel_hi:[0,1,1]
	v_add_f32_e32 v18, v30, v31
	v_add_f32_e32 v94, v38, v39
	v_pk_mul_f32 v[20:21], v[20:21], v[40:41]
	v_add_f32_dpp v0, v18, v18 quad_perm:[1,0,3,2] row_mask:0xf bank_mask:0xf bound_ctrl:1
	v_pk_fma_f32 v[56:57], v[84:85], v[24:25], v[20:21] op_sel_hi:[0,1,1]
	ds_read_b128 v[18:21], v90 offset:3328
	v_add_f32_dpp v0, v0, v0 quad_perm:[2,3,0,1] row_mask:0xf bank_mask:0xf bound_ctrl:1
	ds_read_b128 v[22:25], v89 offset:7424
	ds_read_b128 v[30:33], v90 offset:7424
	v_add_f32_dpp v0, v0, v0 row_half_mirror row_mask:0xf bank_mask:0xf bound_ctrl:1
	ds_read_b128 v[38:41], v90 offset:11520
	ds_read_b128 v[42:45], v89 offset:19712
	v_add_f32_dpp v0, v0, v0 row_ror:8 row_mask:0xf bank_mask:0xf bound_ctrl:1
	s_waitcnt lgkmcnt(11)
	v_pk_fma_f32 v[34:35], v[34:35], v[0:1], v[54:55] op_sel_hi:[1,0,1] neg_lo:[1,0,0] neg_hi:[1,0,0]
	v_pk_fma_f32 v[36:37], v[36:37], v[0:1], v[56:57] op_sel_hi:[1,0,1] neg_lo:[1,0,0] neg_hi:[1,0,0]
	s_waitcnt lgkmcnt(7)
	v_pk_mul_f32 v[14:15], v[14:15], v[34:35]
	v_pk_mul_f32 v[48:49], v[48:49], v[36:37]
	v_pk_mul_f32 v[6:7], v[6:7], v[34:35]
	v_pk_fma_f32 v[34:35], v[46:47], v[34:35], v[48:49]
	v_pk_fma_f32 v[14:15], v[16:17], v[36:37], v[14:15]
	v_pk_fma_f32 v[54:55], v[2:3], v[10:11], v[6:7] op_sel_hi:[0,1,1]
	v_add_f32_e32 v95, v34, v35
	v_add_f32_e32 v6, v14, v15
	ds_write_b128 v91, v[92:95] offset:51200
	v_pk_mul_f32 v[8:9], v[8:9], v[36:37]
	v_add_f32_dpp v0, v6, v6 quad_perm:[1,0,3,2] row_mask:0xf bank_mask:0xf bound_ctrl:1
	v_pk_fma_f32 v[56:57], v[2:3], v[12:13], v[8:9] op_sel_hi:[0,1,1]
	ds_read_b128 v[6:9], v90 offset:3584
	v_add_f32_dpp v0, v0, v0 quad_perm:[2,3,0,1] row_mask:0xf bank_mask:0xf bound_ctrl:1
	ds_read_b128 v[10:13], v89 offset:7680
	ds_read_b128 v[14:17], v90 offset:7680
	v_add_f32_dpp v0, v0, v0 row_half_mirror row_mask:0xf bank_mask:0xf bound_ctrl:1
	ds_read_b128 v[34:37], v90 offset:11776
	ds_read_b128 v[46:49], v89 offset:19968
	v_add_f32_dpp v0, v0, v0 row_ror:8 row_mask:0xf bank_mask:0xf bound_ctrl:1
	s_waitcnt lgkmcnt(12)
	v_pk_fma_f32 v[26:27], v[26:27], v[0:1], v[54:55] op_sel_hi:[1,0,1] neg_lo:[1,0,0] neg_hi:[1,0,0]
	v_pk_fma_f32 v[28:29], v[28:29], v[0:1], v[56:57] op_sel_hi:[1,0,1] neg_lo:[1,0,0] neg_hi:[1,0,0]
	s_waitcnt lgkmcnt(8)
	v_pk_mul_f32 v[30:31], v[30:31], v[26:27]
	v_pk_mul_f32 v[52:53], v[52:53], v[28:29]
	v_pk_mul_f32 v[18:19], v[18:19], v[26:27]
	v_pk_mul_f32 v[20:21], v[20:21], v[28:29]
	v_pk_fma_f32 v[26:27], v[50:51], v[26:27], v[52:53]
	v_pk_fma_f32 v[28:29], v[32:33], v[28:29], v[30:31]
	v_pk_fma_f32 v[54:55], v[2:3], v[22:23], v[18:19] op_sel:[1,0,0]
	v_add_f32_e32 v18, v28, v29
	v_add_f32_e32 v96, v26, v27
	v_pk_fma_f32 v[2:3], v[2:3], v[24:25], v[20:21] op_sel:[1,0,0]
	v_add_f32_dpp v0, v18, v18 quad_perm:[1,0,3,2] row_mask:0xf bank_mask:0xf bound_ctrl:1
	ds_read_b128 v[18:21], v90 offset:3840
	ds_read_b128 v[22:25], v89 offset:7936
	v_add_f32_dpp v0, v0, v0 quad_perm:[2,3,0,1] row_mask:0xf bank_mask:0xf bound_ctrl:1
	ds_read_b128 v[26:29], v90 offset:7936
	ds_read_b128 v[30:33], v90 offset:12032
	v_add_f32_dpp v0, v0, v0 row_half_mirror row_mask:0xf bank_mask:0xf bound_ctrl:1
	ds_read_b128 v[50:53], v89 offset:20224
	s_nop 0
	v_add_f32_dpp v0, v0, v0 row_ror:8 row_mask:0xf bank_mask:0xf bound_ctrl:1
	s_waitcnt lgkmcnt(12)
	v_pk_fma_f32 v[38:39], v[38:39], v[0:1], v[54:55] op_sel_hi:[1,0,1] neg_lo:[1,0,0] neg_hi:[1,0,0]
	v_pk_fma_f32 v[2:3], v[40:41], v[0:1], v[2:3] op_sel_hi:[1,0,1] neg_lo:[1,0,0] neg_hi:[1,0,0]
	s_waitcnt lgkmcnt(7)
	v_pk_mul_f32 v[14:15], v[14:15], v[38:39]
	v_pk_mul_f32 v[40:41], v[44:45], v[2:3]
	v_pk_mul_f32 v[8:9], v[8:9], v[2:3]
	v_pk_fma_f32 v[2:3], v[16:17], v[2:3], v[14:15]
	v_pk_mul_f32 v[6:7], v[6:7], v[38:39]
	v_add_f32_e32 v0, v2, v3
	v_pk_fma_f32 v[6:7], v[4:5], v[10:11], v[6:7] op_sel_hi:[0,1,1]
	v_pk_fma_f32 v[4:5], v[4:5], v[12:13], v[8:9] op_sel_hi:[0,1,1]
	v_add_f32_dpp v0, v0, v0 quad_perm:[1,0,3,2] row_mask:0xf bank_mask:0xf bound_ctrl:1
	v_pk_fma_f32 v[38:39], v[42:43], v[38:39], v[40:41]
	ds_read_b128 v[108:111], v88 offset:4096
	v_add_f32_dpp v0, v0, v0 quad_perm:[2,3,0,1] row_mask:0xf bank_mask:0xf bound_ctrl:1
	v_add_f32_e32 v97, v38, v39
	ds_read_b128 v[100:103], v88
	v_add_f32_dpp v0, v0, v0 row_half_mirror row_mask:0xf bank_mask:0xf bound_ctrl:1
	ds_read_b128 v[120:123], v88 offset:8192
	ds_read_b128 v[112:115], v88 offset:4352
	v_add_f32_dpp v0, v0, v0 row_ror:8 row_mask:0xf bank_mask:0xf bound_ctrl:1
	s_waitcnt lgkmcnt(10)
	v_pk_fma_f32 v[2:3], v[34:35], v[0:1], v[6:7] op_sel_hi:[1,0,1] neg_lo:[1,0,0] neg_hi:[1,0,0]
	v_pk_fma_f32 v[4:5], v[36:37], v[0:1], v[4:5] op_sel_hi:[1,0,1] neg_lo:[1,0,0] neg_hi:[1,0,0]
	s_waitcnt lgkmcnt(6)
	v_pk_mul_f32 v[8:9], v[26:27], v[2:3]
	v_pk_mul_f32 v[6:7], v[48:49], v[4:5]
	v_pk_mul_f32 v[10:11], v[18:19], v[2:3]
	v_pk_mul_f32 v[12:13], v[20:21], v[4:5]
	v_pk_fma_f32 v[2:3], v[46:47], v[2:3], v[6:7]
	v_pk_fma_f32 v[4:5], v[28:29], v[4:5], v[8:9]
	v_add_f32_e32 v98, v2, v3
	v_add_f32_e32 v2, v4, v5
	v_pk_fma_f32 v[8:9], v[86:87], v[24:25], v[12:13] op_sel_hi:[0,1,1]
	s_nop 0
	v_add_f32_dpp v0, v2, v2 quad_perm:[1,0,3,2] row_mask:0xf bank_mask:0xf bound_ctrl:1
	v_pk_fma_f32 v[6:7], v[86:87], v[22:23], v[10:11] op_sel_hi:[0,1,1]
	ds_read_b128 v[104:107], v88 offset:256
	v_add_f32_dpp v0, v0, v0 quad_perm:[2,3,0,1] row_mask:0xf bank_mask:0xf bound_ctrl:1
	ds_read_b128 v[128:131], v88 offset:8448
	ds_read_b128 v[124:127], v88 offset:4608
	v_add_f32_dpp v0, v0, v0 row_half_mirror row_mask:0xf bank_mask:0xf bound_ctrl:1
	ds_read_b128 v[116:119], v88 offset:512
	s_nop 0
	v_add_f32_dpp v0, v0, v0 row_ror:8 row_mask:0xf bank_mask:0xf bound_ctrl:1
	s_waitcnt lgkmcnt(9)
	v_pk_fma_f32 v[76:77], v[32:33], v[0:1], v[8:9] op_sel_hi:[1,0,1] neg_lo:[1,0,0] neg_hi:[1,0,0]
	v_pk_fma_f32 v[74:75], v[30:31], v[0:1], v[6:7] op_sel_hi:[1,0,1] neg_lo:[1,0,0] neg_hi:[1,0,0]
	s_waitcnt lgkmcnt(8)
	v_pk_mul_f32 v[2:3], v[52:53], v[76:77]
	s_nop 0
	v_pk_fma_f32 v[2:3], v[50:51], v[74:75], v[2:3]
	s_nop 0
	v_add_f32_e32 v99, v2, v3
	ds_write_b128 v91, v[96:99] offset:55296
	s_and_b32 s2, s26, 1
	s_mul_i32 s3, s2, 0x5400
	v_lshlrev_b32_e32 v91, 2, v87
	v_lshl_add_u32 v91, s2, 14, v91
	s_add_i32 s2, s3, 0
	v_add_u32_e32 v0, s2, v85
	v_add_u32_e32 v89, s2, v83
	v_add_u32_e32 v90, s96, v83
	s_add_i32 s96, s96, 0x3000
	s_cmp_eq_u32 s96, 0x1e800
	s_cselect_b32 s96, 0x20200, s96
	s_cmp_eq_u32 s96, 0x23200
	s_cselect_b32 s96, 0x12800, s96
	v_add_u32_e32 v88, s96, v83
	s_cmpk_eq_i32 s26, 0x110
	s_waitcnt lgkmcnt(0)
	s_cbranch_scc0 .LBB0_1050
	s_barrier
	s_setprio 0
